# mprep gate scans: wave-level DPP inclusive scans with one LDS exchange each, replacing two 8-step LDS Hillis-Steele scans (32 workgroup barriers); on top of v62
# speedup vs baseline: 1.0112x; 1.0048x over previous
.LBB0_264:
	s_or_b64 exec, exec, s[6:7]
	v_lshrrev_b32_e32 v5, 6, v96
	v_lshlrev_b32_e32 v5, 2, v5
	v_add_u32_e32 v5, 0x21800, v5
	v_readfirstlane_b32 s99, v96
	s_lshr_b32 s99, s99, 6
	s_nop 2
	s_nop 1
	v_add_f32_dpp v3, v3, v3 row_shr:1 row_mask:0xf bank_mask:0xf
	s_nop 1
	v_add_f32_dpp v3, v3, v3 row_shr:2 row_mask:0xf bank_mask:0xf
	s_nop 1
	v_add_f32_dpp v3, v3, v3 row_shr:4 row_mask:0xf bank_mask:0xf
	s_nop 1
	v_add_f32_dpp v3, v3, v3 row_shr:8 row_mask:0xf bank_mask:0xf
	s_nop 1
	v_add_f32_dpp v3, v3, v3 row_bcast:15 row_mask:0xa bank_mask:0xf
	s_nop 1
	v_add_f32_dpp v3, v3, v3 row_bcast:31 row_mask:0xc bank_mask:0xf
	s_nop 1
	v_readlane_b32 s98, v3, 63
	s_nop 3
	v_mov_b32_e32 v6, s98
	ds_write_b32 v5, v6
	s_waitcnt lgkmcnt(0)
	s_barrier
	v_mov_b32_e32 v7, 0x21800
	ds_read_b128 v[100:103], v7
	s_waitcnt lgkmcnt(0)
	v_add_f32_e32 v101, v100, v101
	v_add_f32_e32 v102, v101, v102
	v_mov_b32_e32 v6, 0
	s_cmp_eq_u32 s99, 1
	s_cselect_b64 s[100:101], -1, 0
	v_cndmask_b32_e64 v6, v6, v100, s[100:101]
	s_cmp_eq_u32 s99, 2
	s_cselect_b64 s[100:101], -1, 0
	v_cndmask_b32_e64 v6, v6, v101, s[100:101]
	s_cmp_eq_u32 s99, 3
	s_cselect_b64 s[100:101], -1, 0
	v_cndmask_b32_e64 v6, v6, v102, s[100:101]
	v_add_f32_e32 v3, v6, v3
	s_waitcnt vmcnt(0)
	v_sub_f32_e32 v4, v2, v3
	v_mov_b32_e32 v2, v4
	s_nop 1
	v_max_f32_dpp v2, v2, v2 row_shr:1 row_mask:0xf bank_mask:0xf
	s_nop 1
	v_max_f32_dpp v2, v2, v2 row_shr:2 row_mask:0xf bank_mask:0xf
	s_nop 1
	v_max_f32_dpp v2, v2, v2 row_shr:4 row_mask:0xf bank_mask:0xf
	s_nop 1
	v_max_f32_dpp v2, v2, v2 row_shr:8 row_mask:0xf bank_mask:0xf
	s_nop 1
	v_max_f32_dpp v2, v2, v2 row_bcast:15 row_mask:0xa bank_mask:0xf
	s_nop 1
	v_max_f32_dpp v2, v2, v2 row_bcast:31 row_mask:0xc bank_mask:0xf
	s_nop 1
	v_readlane_b32 s98, v2, 63
	s_nop 3
	v_mov_b32_e32 v6, s98
	ds_write_b32 v5, v6 offset:32
	s_waitcnt lgkmcnt(0)
	s_barrier
	ds_read_b128 v[100:103], v7 offset:32
	s_waitcnt lgkmcnt(0)
	v_max_f32_e32 v101, v100, v101
	v_max_f32_e32 v102, v101, v102
	v_mov_b32_e32 v6, 0xff800000
	s_cmp_eq_u32 s99, 1
	s_cselect_b64 s[100:101], -1, 0
	v_cndmask_b32_e64 v6, v6, v100, s[100:101]
	s_cmp_eq_u32 s99, 2
	s_cselect_b64 s[100:101], -1, 0
	v_cndmask_b32_e64 v6, v6, v101, s[100:101]
	s_cmp_eq_u32 s99, 3
	s_cselect_b64 s[100:101], -1, 0
	v_cndmask_b32_e64 v6, v6, v102, s[100:101]
	v_max_f32_e32 v2, v6, v2
	v_cmp_eq_u32_e32 vcc, 0xff, v96
	s_and_saveexec_b64 s[6:7], vcc
	v_mov_b32_e32 v6, s88
	v_mov_b32_e32 v7, s87
	ds_write_b32 v6, v3
	ds_write_b32 v7, v2
	s_or_b64 exec, exec, s[6:7]
	v_mov_b32_e32 v5, s87
	s_waitcnt lgkmcnt(0)
	s_barrier
	v_mov_b32_e32 v7, s88
	ds_read_b32 v6, v5
	ds_read_b32 v5, v7
	s_and_saveexec_b64 s[6:7], s[4:5]
	s_cbranch_execz .LBB0_332
	v_lshlrev_b64 v[0:1], 4, v[0:1]
	v_lshl_or_b32 v0, s2, 2, v0
	v_lshl_add_u64 v[8:9], s[62:63], 0, v[0:1]
	global_store_dword v[8:9], v3, off
	s_waitcnt lgkmcnt(1)
	v_sub_f32_e32 v3, v4, v6
	v_mul_f32_e32 v3, 0x3fb8aa3b, v3
	v_exp_f32_e32 v3, v3
	v_lshl_add_u64 v[8:9], s[74:75], 0, v[0:1]
	v_lshl_add_u64 v[0:1], s[28:29], 0, v[0:1]
	global_store_dword v[0:1], v2, off
	v_add_u32_e32 v0, 0x21800, v97
	global_store_dword v[8:9], v4, off
	ds_write_b32 v0, v3

.LBB0_399:
	v_add_u32_e32 v2, 0xffffffa0, v4
	ds_read_b64_tr_b16 v[6:7], v2 offset:0
	ds_read_b64_tr_b16 v[8:9], v2 offset:0x840
	v_subrev_u32_e32 v2, 64, v4
	ds_read_b64_tr_b16 v[10:11], v2 offset:0
	ds_read_b64_tr_b16 v[12:13], v2 offset:0x840
	v_subrev_u32_e32 v2, 32, v4
	ds_read_b64_tr_b16 v[14:15], v2 offset:0
	ds_read_b64_tr_b16 v[16:17], v2 offset:0x840
	ds_read_b64_tr_b16 v[18:19], v4 offset:0
	ds_read_b64_tr_b16 v[20:21], v4 offset:0x840
	s_waitcnt lgkmcnt(0)
	v_lshl_add_u64 v[2:3], v[0:1], 0, s[4:5]
	s_mov_b32 s0, 0x6000000
	v_add_co_u32_e32 v22, vcc, s0, v2
	s_mov_b32 s1, 0x6002000
	s_nop 0
	v_addc_co_u32_e32 v23, vcc, 0, v3, vcc
	v_add_co_u32_e32 v24, vcc, s1, v2
	s_mov_b32 s2, 0x6004000
	s_nop 0
	v_addc_co_u32_e32 v25, vcc, 0, v3, vcc
	v_add_co_u32_e32 v26, vcc, s2, v2
	s_mov_b32 s3, 0x6006000
	s_add_u32 s4, s4, 0x8000
	v_addc_co_u32_e32 v27, vcc, 0, v3, vcc
	s_addc_u32 s5, s5, 0
	v_add_co_u32_e32 v2, vcc, s3, v2
	v_add_u32_e32 v4, 0x80, v4
	s_cmp_lg_u32 s4, 0x20000
	v_addc_co_u32_e32 v3, vcc, 0, v3, vcc
	global_store_dwordx4 v[22:23], v[6:9], off
	global_store_dwordx4 v[24:25], v[10:13], off
	global_store_dwordx4 v[26:27], v[14:17], off
	global_store_dwordx4 v[2:3], v[18:21], off
	s_cbranch_scc1 .LBB0_399
	v_mov_b32_e32 v1, v182
	v_mov_b32_e32 v0, v182
	v_mov_b32_e32 v14, v182
	s_waitcnt vmcnt(0)
	s_barrier
	s_add_u32 s8, s85, s6
	v_bfe_i32 v3, v14, 27, 1
	v_lshlrev_b32_e32 v2, 4, v14
	v_lshrrev_b32_e32 v3, 22, v3
	v_add_u32_e32 v3, v2, v3
	v_and_b32_e32 v3, 0xfffffc00, v3
	v_sub_u32_e32 v3, v2, v3
	v_ashrrev_i32_e32 v0, 31, v14
	v_lshrrev_b32_e32 v4, 4, v3
	v_lshrrev_b32_e32 v0, 26, v0
	v_bitop3_b32 v4, v4, v3, 32 bitop3:0x6c
	v_ashrrev_i32_e32 v3, 31, v3
	v_add_u32_e32 v0, v14, v0
	v_lshrrev_b32_e32 v3, 26, v3
	v_ashrrev_i32_e32 v0, 6, v0
	v_add_u32_e32 v3, v4, v3
	v_lshlrev_b32_e32 v5, 3, v0
	v_ashrrev_i32_e32 v3, 6, v3
	v_and_b32_e32 v5, -16, v5
	v_mul_i32_i24_e32 v6, 64, v3
	v_add_u32_e32 v5, v3, v5
	v_sub_u32_e32 v4, v4, v6
	v_lshlrev_b32_e32 v0, 5, v0
	v_ashrrev_i16_sdwa v4, v151, sext(v4) dst_sel:DWORD dst_unused:UNUSED_PAD src0_sel:DWORD src1_sel:BYTE_0
	v_lshlrev_b32_e32 v6, 1, v5
	v_lshrrev_b32_e32 v7, 2, v5
	v_and_b32_e32 v3, 3, v3
	v_and_b32_e32 v0, 32, v0
	v_bfe_i32 v4, v4, 0, 16
	v_and_b32_e32 v6, 24, v6
	v_and_b32_e32 v7, 4, v7
	v_and_or_b32 v3, v5, s92, v3
	v_or3_b32 v3, v3, v7, v6
	v_add_lshl_u32 v4, v0, v4, 1
	v_add_u32_e32 v2, 0x2000, v2
	v_lshl_add_u32 v128, v3, 9, v4
	v_ashrrev_i32_e32 v3, 31, v2
	v_lshrrev_b32_e32 v3, 22, v3
	v_add_u32_e32 v3, v2, v3
	v_ashrrev_i32_e32 v3, 10, v3
	v_lshl_add_u32 v0, v5, 9, v4
	v_mul_i32_i24_e32 v4, 0x400, v3
	v_sub_u32_e32 v2, v2, v4
	v_lshrrev_b32_e32 v4, 4, v2
	v_bitop3_b32 v2, v4, v2, 32 bitop3:0x6c
	v_ashrrev_i32_e32 v5, 31, v2
	v_lshrrev_b32_e32 v5, 26, v5
	s_addc_u32 s9, s86, s7
	v_readlane_b32 s0, v252, 27
	v_lshlrev_b32_e32 v4, 3, v3
	v_add_u32_e32 v5, v2, v5
	v_readlane_b32 s1, v252, 28
	s_add_u32 s4, s0, s6
	v_readfirstlane_b32 s0, v14
	v_and_b32_e32 v4, -16, v4
	v_ashrrev_i32_e32 v6, 6, v5
	v_and_b32_e32 v5, 0xc0, v5
	s_addc_u32 s5, s1, s7
	v_add_u32_e32 v4, v6, v4
	v_sub_u32_e32 v2, v2, v5
	s_ashr_i32 s3, s0, 6
	v_lshlrev_b32_e32 v3, 5, v3
	v_ashrrev_i16_sdwa v2, v151, sext(v2) dst_sel:DWORD dst_unused:UNUSED_PAD src0_sel:DWORD src1_sel:BYTE_0
	v_lshlrev_b32_e32 v5, 1, v4
	v_lshrrev_b32_e32 v7, 2, v4
	v_and_b32_e32 v6, 3, v6
	s_lshl_b32 s33, s3, 10
	v_and_b32_e32 v3, 32, v3
	v_bfe_i32 v2, v2, 0, 16
	v_and_b32_e32 v5, 24, v5
	v_and_b32_e32 v7, 4, v7
	v_and_or_b32 v6, v4, s92, v6
	s_add_i32 s41, s33, 0
	v_or3_b32 v5, v6, v7, v5
	v_add_lshl_u32 v3, v3, v2, 1
	s_add_i32 m0, s41, 0x10000
	v_lshl_add_u32 v2, v4, 9, v3
	v_lshl_add_u32 v4, v5, 9, v3
	global_load_lds_dwordx4 v128, s[4:5]
	s_add_i32 m0, s41, 0x12000
	s_ashr_i32 s2, s0, 8
	global_load_lds_dwordx4 v4, s[4:5]
	s_mov_b32 m0, s41
	s_add_i32 s42, s41, 0x2000
	global_load_lds_dwordx4 v0, s[8:9]
	s_mov_b32 m0, s42
	s_add_u32 s6, s4, 0x10000
	global_load_lds_dwordx4 v2, s[8:9]
	s_addc_u32 s7, s5, 0
	s_add_i32 m0, s41, 0x14000
	v_readfirstlane_b32 s1, v1
	global_load_lds_dwordx4 v128, s[6:7]
	s_add_i32 m0, s41, 0x16000
	v_mov_b32_e32 v5, v129
	global_load_lds_dwordx4 v4, s[6:7]
	s_add_u32 s6, s8, 0x10000
	s_addc_u32 s7, s9, 0
	s_add_i32 s40, s41, 0x4000
	s_mov_b32 m0, s40
	s_add_i32 s18, s41, 0x6000
	global_load_lds_dwordx4 v0, s[6:7]
	s_mov_b32 m0, s18
	v_mov_b32_e32 v1, v129
	global_load_lds_dwordx4 v2, s[6:7]
	v_mov_b32_e32 v3, v129
	v_lshl_add_u64 v[12:13], s[4:5], 0, v[128:129]
	v_lshl_add_u64 v[10:11], s[4:5], 0, v[4:5]
	v_lshl_add_u64 v[6:7], s[8:9], 0, v[0:1]
	s_cmp_lg_u32 s2, 1
	v_lshl_add_u64 v[8:9], s[8:9], 0, v[2:3]
	s_cbranch_scc1 .LBB0_402
	s_barrier
	s_branch .Lpadskip_1
	s_nop 0
	s_nop 0
	s_nop 0
	s_nop 0
	s_nop 0
	s_nop 0
	s_nop 0
	s_nop 0
	s_nop 0
	s_nop 0
	s_nop 0
